# prep conversion loop + ret_intra V loads widened to dwordx4 with permlane32_swap (half the VMEM instructions)
# speedup vs baseline: 1.0034x; 1.0034x over previous
.LBB0_450:
	s_andn2_saveexec_b64 s[4:5], s[70:71]
	v_cvt_f32_u32_e32 v20, v38
	v_mul_f32_e32 v20, v23, v20
	v_exp_f32_e32 v37, v20
	s_or_b64 exec, exec, s[4:5]
	v_mul_f32_e32 v8, v8, v28
	v_mul_f32_e32 v9, v9, v29
	v_mul_f32_e32 v6, v6, v26
	v_mul_f32_e32 v7, v7, v27
	v_mul_f32_e32 v4, v4, v24
	v_mul_f32_e32 v5, v5, v25
	v_mul_f32_e32 v2, v2, v19
	v_mul_f32_e32 v3, v3, v22
	v_mul_f32_e32 v16, v16, v36
	v_mul_f32_e32 v14, v14, v34
	v_mul_f32_e32 v15, v15, v35
	v_mul_f32_e32 v12, v12, v32
	v_mul_f32_e32 v13, v13, v33
	v_mul_f32_e32 v10, v10, v30
	v_mul_f32_e32 v11, v11, v31
	v_mul_f32_e32 v17, v17, v37
	v_cvt_pk_bf16_f32 v2, v2, v3
	v_cvt_pk_bf16_f32 v3, v4, v5
	v_cvt_pk_bf16_f32 v4, v6, v7
	v_cvt_pk_bf16_f32 v5, v8, v9
	v_or_b32_e32 v75, v0, v190
	s_barrier
	v_cvt_pk_bf16_f32 v6, v10, v11
	v_cvt_pk_bf16_f32 v7, v12, v13
	v_cvt_pk_bf16_f32 v8, v14, v15
	v_cvt_pk_bf16_f32 v9, v16, v17
	ds_write_b128 v191, v[2:5]
	ds_write_b128 v191, v[6:9] offset:1024
	v_or_b32_e32 v2, v75, v71
	v_lshlrev_b32_e32 v34, 14, v2
	v_mov_b32_e32 v35, v1
	v_ashrrev_i32_e32 v19, 31, v18
	v_lshl_add_u64 v[2:3], s[62:63], 0, v[34:35]
	v_lshlrev_b64 v[36:37], 1, v[18:19]
	v_lshl_add_u64 v[2:3], v[2:3], 0, v[36:37]
	v_lshl_add_u64 v[36:37], v[68:69], 0, v[36:37]
	v_lshl_add_u64 v[156:157], v[36:37], 0, v[34:35]
	v_bfe_u32 v36, v189, 5, 1
	v_lshlrev_b32_e32 v36, 3, v36
	v_mov_b32_e32 v37, 0
	v_lshl_add_u64 v[156:157], v[156:157], 0, v[36:37]
	s_mov_b32 s4, 0x80000
	v_mov_b32_e32 v77, v1
	v_add_co_u32_e64 v38, s[4:5], s4, v156
	v_lshl_add_u64 v[32:33], v[2:3], 0, v[76:77]
	v_lshl_add_u64 v[32:33], v[32:33], 0, v[36:37]
	s_nop 0
	v_addc_co_u32_e64 v39, s[4:5], 0, v157, s[4:5]
	s_waitcnt lgkmcnt(0)
	s_barrier
	global_load_dwordx4 v[2:5], v[32:33], off
	global_load_dwordx4 v[6:9], v[32:33], off offset:32
	global_load_dwordx4 v[10:13], v[32:33], off offset:64
	global_load_dwordx4 v[14:17], v[32:33], off offset:96
	global_load_dwordx4 v[18:21], v[32:33], off offset:128
	global_load_dwordx4 v[22:25], v[32:33], off offset:160
	global_load_dwordx4 v[26:29], v[32:33], off offset:192
	global_load_dwordx4 v[30:33], v[32:33], off offset:224
	global_load_dwordx4 v[34:37], v[38:39], off
	global_load_dwordx4 v[80:83], v[38:39], off offset:32
	global_load_dwordx4 v[84:87], v[38:39], off offset:64
	global_load_dwordx4 v[88:91], v[38:39], off offset:96
	global_load_dwordx4 v[92:95], v[38:39], off offset:128
	global_load_dwordx4 v[96:99], v[38:39], off offset:160
	global_load_dwordx4 v[100:103], v[38:39], off offset:192
	global_load_dwordx4 v[104:107], v[38:39], off offset:224
	ds_read_b128 v[108:111], v181
	ds_read_b128 v[112:115], v181 offset:1024
	ds_read_b128 v[116:119], v181 offset:2048
	ds_read_b128 v[120:123], v181 offset:3072
	ds_read_b128 v[124:127], v181 offset:4096
	ds_read_b128 v[128:131], v181 offset:5120
	ds_read_b128 v[132:135], v181 offset:6144
	ds_read_b128 v[136:139], v181 offset:7168
	s_waitcnt vmcnt(15)
	v_permlane32_swap_b32_e32 v2, v4
	v_permlane32_swap_b32_e32 v3, v5
	s_waitcnt vmcnt(14)
	v_permlane32_swap_b32_e32 v6, v8
	v_permlane32_swap_b32_e32 v7, v9
	s_waitcnt lgkmcnt(7)
	v_mfma_f32_32x32x16_bf16 v[50:65], v[2:5], v[108:111], 0
	s_waitcnt vmcnt(13)
	v_permlane32_swap_b32_e32 v10, v12
	v_permlane32_swap_b32_e32 v11, v13
	s_waitcnt lgkmcnt(6)
	v_mfma_f32_32x32x16_bf16 v[50:65], v[6:9], v[112:115], v[50:65]
	s_waitcnt vmcnt(12)
	v_permlane32_swap_b32_e32 v14, v16
	v_permlane32_swap_b32_e32 v15, v17
	s_waitcnt lgkmcnt(5)
	v_mfma_f32_32x32x16_bf16 v[50:65], v[10:13], v[116:119], v[50:65]
	s_waitcnt vmcnt(11)
	v_permlane32_swap_b32_e32 v18, v20
	v_permlane32_swap_b32_e32 v19, v21
	s_waitcnt lgkmcnt(4)
	v_mfma_f32_32x32x16_bf16 v[50:65], v[14:17], v[120:123], v[50:65]
	s_waitcnt vmcnt(10)
	v_permlane32_swap_b32_e32 v22, v24
	v_permlane32_swap_b32_e32 v23, v25
	s_waitcnt lgkmcnt(3)
	v_mfma_f32_32x32x16_bf16 v[50:65], v[18:21], v[124:127], v[50:65]
	s_waitcnt vmcnt(9)
	v_permlane32_swap_b32_e32 v26, v28
	v_permlane32_swap_b32_e32 v27, v29
	s_waitcnt lgkmcnt(2)
	v_mfma_f32_32x32x16_bf16 v[50:65], v[22:25], v[128:131], v[50:65]
	s_waitcnt vmcnt(8)
	v_permlane32_swap_b32_e32 v30, v32
	v_permlane32_swap_b32_e32 v31, v33
	s_waitcnt lgkmcnt(1)
	v_mfma_f32_32x32x16_bf16 v[50:65], v[26:29], v[132:135], v[50:65]
	s_nop 1
	s_waitcnt lgkmcnt(0)
	v_mfma_f32_32x32x16_bf16 v[50:65], v[30:33], v[136:139], v[50:65]
	s_mov_b32 s4, 0x100000
	v_add_co_u32_e64 v18, s[4:5], s4, v156
	s_nop 1
	v_addc_co_u32_e64 v19, s[4:5], 0, v157, s[4:5]
	global_load_dwordx4 v[2:5], v[18:19], off
	global_load_dwordx4 v[6:9], v[18:19], off offset:32
	global_load_dwordx4 v[10:13], v[18:19], off offset:64
	global_load_dwordx4 v[14:17], v[18:19], off offset:96
	global_load_dwordx4 v[140:143], v[18:19], off offset:128
	global_load_dwordx4 v[144:147], v[18:19], off offset:160
	global_load_dwordx4 v[148:151], v[18:19], off offset:192
	global_load_dwordx4 v[152:155], v[18:19], off offset:224
	s_waitcnt vmcnt(15)
	v_permlane32_swap_b32_e32 v34, v36
	v_permlane32_swap_b32_e32 v35, v37
	s_waitcnt vmcnt(14)
	v_permlane32_swap_b32_e32 v80, v82
	v_permlane32_swap_b32_e32 v81, v83
	s_waitcnt lgkmcnt(7)
	v_mfma_f32_32x32x16_bf16 v[34:49], v[34:37], v[108:111], 0
	s_waitcnt vmcnt(13)
	v_permlane32_swap_b32_e32 v84, v86
	v_permlane32_swap_b32_e32 v85, v87
	s_waitcnt lgkmcnt(6)
	v_mfma_f32_32x32x16_bf16 v[34:49], v[80:83], v[112:115], v[34:49]
	s_waitcnt vmcnt(12)
	v_permlane32_swap_b32_e32 v88, v90
	v_permlane32_swap_b32_e32 v89, v91
	s_waitcnt lgkmcnt(5)
	v_mfma_f32_32x32x16_bf16 v[34:49], v[84:87], v[116:119], v[34:49]
	s_waitcnt vmcnt(11)
	v_permlane32_swap_b32_e32 v92, v94
	v_permlane32_swap_b32_e32 v93, v95
	s_waitcnt lgkmcnt(4)
	v_mfma_f32_32x32x16_bf16 v[34:49], v[88:91], v[120:123], v[34:49]
	s_waitcnt vmcnt(10)
	v_permlane32_swap_b32_e32 v96, v98
	v_permlane32_swap_b32_e32 v97, v99
	s_waitcnt lgkmcnt(3)
	v_mfma_f32_32x32x16_bf16 v[34:49], v[92:95], v[124:127], v[34:49]
	s_waitcnt vmcnt(9)
	v_permlane32_swap_b32_e32 v100, v102
	v_permlane32_swap_b32_e32 v101, v103
	s_waitcnt lgkmcnt(2)
	v_mfma_f32_32x32x16_bf16 v[34:49], v[96:99], v[128:131], v[34:49]
	s_waitcnt vmcnt(8)
	v_permlane32_swap_b32_e32 v104, v106
	v_permlane32_swap_b32_e32 v105, v107
	s_waitcnt lgkmcnt(1)
	v_mfma_f32_32x32x16_bf16 v[34:49], v[100:103], v[132:135], v[34:49]
	s_nop 1
	s_waitcnt lgkmcnt(0)
	v_mfma_f32_32x32x16_bf16 v[34:49], v[104:107], v[136:139], v[34:49]
	s_mov_b32 s4, 0x180000
	v_add_co_u32_e64 v18, s[4:5], s4, v156
	s_nop 1
	v_addc_co_u32_e64 v19, s[4:5], 0, v157, s[4:5]
	global_load_dwordx4 v[80:83], v[18:19], off
	global_load_dwordx4 v[84:87], v[18:19], off offset:32
	global_load_dwordx4 v[88:91], v[18:19], off offset:64
	global_load_dwordx4 v[92:95], v[18:19], off offset:96
	global_load_dwordx4 v[96:99], v[18:19], off offset:128
	global_load_dwordx4 v[100:103], v[18:19], off offset:160
	global_load_dwordx4 v[104:107], v[18:19], off offset:192
	global_load_dwordx4 v[156:159], v[18:19], off offset:224
	s_waitcnt vmcnt(15)
	v_permlane32_swap_b32_e32 v2, v4
	v_permlane32_swap_b32_e32 v3, v5
	s_waitcnt vmcnt(14)
	v_permlane32_swap_b32_e32 v6, v8
	v_permlane32_swap_b32_e32 v7, v9
	s_waitcnt lgkmcnt(7)
	v_mfma_f32_32x32x16_bf16 v[18:33], v[2:5], v[108:111], 0
	s_waitcnt vmcnt(13)
	v_permlane32_swap_b32_e32 v10, v12
	v_permlane32_swap_b32_e32 v11, v13
	s_waitcnt lgkmcnt(6)
	v_mfma_f32_32x32x16_bf16 v[18:33], v[6:9], v[112:115], v[18:33]
	s_waitcnt vmcnt(12)
	v_permlane32_swap_b32_e32 v14, v16
	v_permlane32_swap_b32_e32 v15, v17
	s_waitcnt lgkmcnt(5)
	v_mfma_f32_32x32x16_bf16 v[18:33], v[10:13], v[116:119], v[18:33]
	s_waitcnt vmcnt(11)
	v_permlane32_swap_b32_e32 v140, v142
	v_permlane32_swap_b32_e32 v141, v143
	s_waitcnt lgkmcnt(4)
	v_mfma_f32_32x32x16_bf16 v[18:33], v[14:17], v[120:123], v[18:33]
	s_waitcnt vmcnt(10)
	v_permlane32_swap_b32_e32 v144, v146
	v_permlane32_swap_b32_e32 v145, v147
	s_waitcnt lgkmcnt(3)
	v_mfma_f32_32x32x16_bf16 v[18:33], v[140:143], v[124:127], v[18:33]
	s_waitcnt vmcnt(9)
	v_permlane32_swap_b32_e32 v148, v150
	v_permlane32_swap_b32_e32 v149, v151
	s_waitcnt lgkmcnt(2)
	v_mfma_f32_32x32x16_bf16 v[18:33], v[144:147], v[128:131], v[18:33]
	s_waitcnt vmcnt(8)
	v_permlane32_swap_b32_e32 v152, v154
	v_permlane32_swap_b32_e32 v153, v155
	s_waitcnt lgkmcnt(1)
	v_mfma_f32_32x32x16_bf16 v[18:33], v[148:151], v[132:135], v[18:33]
	s_waitcnt vmcnt(7)
	v_permlane32_swap_b32_e32 v80, v82
	v_permlane32_swap_b32_e32 v81, v83
	s_waitcnt lgkmcnt(0)
	v_mfma_f32_32x32x16_bf16 v[18:33], v[152:155], v[136:139], v[18:33]
	s_waitcnt vmcnt(6)
	v_permlane32_swap_b32_e32 v84, v86
	v_permlane32_swap_b32_e32 v85, v87
	s_waitcnt lgkmcnt(7)
	v_mfma_f32_32x32x16_bf16 v[2:17], v[80:83], v[108:111], 0
	s_waitcnt vmcnt(5)
	v_permlane32_swap_b32_e32 v88, v90
	v_permlane32_swap_b32_e32 v89, v91
	s_waitcnt lgkmcnt(6)
	v_mfma_f32_32x32x16_bf16 v[2:17], v[84:87], v[112:115], v[2:17]
	s_waitcnt vmcnt(4)
	v_permlane32_swap_b32_e32 v92, v94
	v_permlane32_swap_b32_e32 v93, v95
	s_waitcnt lgkmcnt(5)
	v_mfma_f32_32x32x16_bf16 v[2:17], v[88:91], v[116:119], v[2:17]
	s_waitcnt vmcnt(3)
	v_permlane32_swap_b32_e32 v96, v98
	v_permlane32_swap_b32_e32 v97, v99
	s_waitcnt lgkmcnt(4)
	v_mfma_f32_32x32x16_bf16 v[2:17], v[92:95], v[120:123], v[2:17]
	s_waitcnt vmcnt(2)
	v_permlane32_swap_b32_e32 v100, v102
	v_permlane32_swap_b32_e32 v101, v103
	s_waitcnt lgkmcnt(3)
	v_mfma_f32_32x32x16_bf16 v[2:17], v[96:99], v[124:127], v[2:17]
	s_waitcnt vmcnt(1)
	v_permlane32_swap_b32_e32 v104, v106
	v_permlane32_swap_b32_e32 v105, v107
	s_waitcnt lgkmcnt(2)
	v_mfma_f32_32x32x16_bf16 v[2:17], v[100:103], v[128:131], v[2:17]
	s_waitcnt vmcnt(0)
	v_permlane32_swap_b32_e32 v156, v158
	v_permlane32_swap_b32_e32 v157, v159
	s_waitcnt lgkmcnt(1)
	v_mfma_f32_32x32x16_bf16 v[2:17], v[104:107], v[132:135], v[2:17]
	s_nop 1
	s_waitcnt lgkmcnt(0)
	v_mfma_f32_32x32x16_bf16 v[2:17], v[156:159], v[136:139], v[2:17]
	v_or_b32_e32 v0, v70, v0
	v_or_b32_e32 v80, v0, v78
	v_mov_b32_e32 v81, v79
	v_lshlrev_b64 v[80:81], 1, v[80:81]
	v_lshl_add_u64 v[82:83], s[64:65], 0, v[80:81]
	v_lshl_add_u64 v[84:85], s[66:67], 0, v[80:81]
	v_lshl_add_u64 v[80:81], s[68:69], 0, v[80:81]
	global_load_dwordx2 v[114:115], v[82:83], off
	global_load_dwordx2 v[118:119], v[82:83], off offset:16
	global_load_dwordx2 v[122:123], v[82:83], off offset:32
	global_load_dwordx2 v[126:127], v[82:83], off offset:48
	global_load_dwordx2 v[116:117], v[84:85], off
	global_load_dwordx2 v[120:121], v[84:85], off offset:16
	global_load_dwordx2 v[124:125], v[84:85], off offset:32
	global_load_dwordx2 v[128:129], v[84:85], off offset:48
	global_load_dwordx2 v[110:111], v[80:81], off
	global_load_dwordx2 v[108:109], v[80:81], off offset:16
	global_load_dwordx2 v[106:107], v[80:81], off offset:32
	global_load_dwordx2 v[104:105], v[80:81], off offset:48
	global_load_dwordx2 v[130:131], v[82:83], off offset:64
	global_load_dwordx2 v[134:135], v[82:83], off offset:80
	global_load_dwordx2 v[138:139], v[82:83], off offset:96
	global_load_dwordx2 v[142:143], v[82:83], off offset:112
	global_load_dwordx2 v[132:133], v[84:85], off offset:64
	global_load_dwordx2 v[136:137], v[84:85], off offset:80
	global_load_dwordx2 v[140:141], v[84:85], off offset:96
	global_load_dwordx2 v[144:145], v[84:85], off offset:112
	global_load_dwordx2 v[102:103], v[80:81], off offset:64
	global_load_dwordx2 v[100:101], v[80:81], off offset:80
	global_load_dwordx2 v[98:99], v[80:81], off offset:96
	global_load_dwordx2 v[96:97], v[80:81], off offset:112
	global_load_dwordx2 v[146:147], v[82:83], off offset:128
	global_load_dwordx2 v[150:151], v[82:83], off offset:144
	global_load_dwordx2 v[154:155], v[82:83], off offset:160
	global_load_dwordx2 v[158:159], v[82:83], off offset:176
	global_load_dwordx2 v[148:149], v[84:85], off offset:128
	global_load_dwordx2 v[152:153], v[84:85], off offset:144
	global_load_dwordx2 v[156:157], v[84:85], off offset:160
	global_load_dwordx2 v[160:161], v[84:85], off offset:176
	global_load_dwordx2 v[94:95], v[80:81], off offset:128
	global_load_dwordx2 v[92:93], v[80:81], off offset:144
	global_load_dwordx2 v[90:91], v[80:81], off offset:160
	global_load_dwordx2 v[88:89], v[80:81], off offset:176
	global_load_dwordx2 v[162:163], v[82:83], off offset:192
	global_load_dwordx2 v[164:165], v[82:83], off offset:208
	global_load_dwordx2 v[168:169], v[82:83], off offset:224
	global_load_dwordx2 v[172:173], v[82:83], off offset:240
	global_load_dwordx2 v[166:167], v[84:85], off offset:192
	global_load_dwordx2 v[170:171], v[84:85], off offset:208
	global_load_dwordx2 v[174:175], v[84:85], off offset:224
	global_load_dwordx2 v[176:177], v[84:85], off offset:240
	global_load_dwordx2 v[86:87], v[80:81], off offset:192
	s_nop 0
	global_load_dwordx2 v[84:85], v[80:81], off offset:208
	global_load_dwordx2 v[82:83], v[80:81], off offset:224
	s_nop 0
	global_load_dwordx2 v[80:81], v[80:81], off offset:240
	s_waitcnt vmcnt(47)
	v_lshlrev_b32_e32 v112, 16, v114
	v_and_b32_e32 v113, 0xffff0000, v114
	s_waitcnt vmcnt(43)
	v_lshlrev_b32_e32 v178, 16, v116
	v_and_b32_e32 v179, 0xffff0000, v116
	v_pk_add_f32 v[112:113], v[112:113], v[178:179]
	v_lshlrev_b32_e32 v114, 16, v117
	v_pk_add_f32 v[112:113], v[50:51], v[112:113]
	v_lshlrev_b32_e32 v50, 16, v115
	v_and_b32_e32 v51, 0xffff0000, v115
	v_and_b32_e32 v115, 0xffff0000, v117
	v_pk_add_f32 v[50:51], v[50:51], v[114:115]
	v_add_f32_e32 v0, 0, v112
	v_pk_add_f32 v[114:115], v[52:53], v[50:51]
	v_add_f32_e32 v52, v113, v0
	v_mul_f32_e32 v0, v113, v113
	v_pk_fma_f32 v[50:51], v[112:113], v[112:113], v[0:1] op_sel_hi:[1,1,0]
	v_add_f32_e32 v0, v114, v52
	v_lshlrev_b32_e32 v52, 16, v118
	v_and_b32_e32 v53, 0xffff0000, v118
	s_waitcnt vmcnt(42)
	v_lshlrev_b32_e32 v116, 16, v120
	v_and_b32_e32 v117, 0xffff0000, v120
	v_pk_add_f32 v[52:53], v[52:53], v[116:117]
	v_pk_fma_f32 v[50:51], v[114:115], v[114:115], v[50:51]
	v_add_f32_e32 v77, v115, v0
	v_mul_f32_e32 v0, v115, v115
	v_pk_add_f32 v[116:117], v[54:55], v[52:53]
	v_lshlrev_b32_e32 v52, 16, v119
	v_and_b32_e32 v53, 0xffff0000, v119
	v_lshlrev_b32_e32 v54, 16, v121
	v_and_b32_e32 v55, 0xffff0000, v121
	v_pk_add_f32 v[50:51], v[0:1], v[50:51] op_sel_hi:[0,1]
	v_pk_add_f32 v[52:53], v[52:53], v[54:55]
	v_add_f32_e32 v0, v116, v77
	v_pk_add_f32 v[118:119], v[56:57], v[52:53]
	v_pk_fma_f32 v[50:51], v[116:117], v[116:117], v[50:51]
	v_add_f32_e32 v52, v117, v0
	v_mul_f32_e32 v0, v117, v117
	v_pk_add_f32 v[50:51], v[0:1], v[50:51] op_sel_hi:[0,1]
	v_add_f32_e32 v0, v118, v52
	v_lshlrev_b32_e32 v52, 16, v122
	v_and_b32_e32 v53, 0xffff0000, v122
	s_waitcnt vmcnt(41)
	v_lshlrev_b32_e32 v54, 16, v124
	v_and_b32_e32 v55, 0xffff0000, v124
	v_pk_add_f32 v[52:53], v[52:53], v[54:55]
	v_pk_fma_f32 v[50:51], v[118:119], v[118:119], v[50:51]
	v_add_f32_e32 v56, v119, v0
	v_mul_f32_e32 v0, v119, v119
	v_pk_add_f32 v[120:121], v[58:59], v[52:53]
	v_lshlrev_b32_e32 v52, 16, v123
	v_and_b32_e32 v53, 0xffff0000, v123
	v_lshlrev_b32_e32 v54, 16, v125
	v_and_b32_e32 v55, 0xffff0000, v125
	v_pk_add_f32 v[50:51], v[0:1], v[50:51] op_sel_hi:[0,1]
	v_pk_add_f32 v[52:53], v[52:53], v[54:55]
	v_add_f32_e32 v0, v120, v56
	v_pk_add_f32 v[122:123], v[60:61], v[52:53]
	v_pk_fma_f32 v[50:51], v[120:121], v[120:121], v[50:51]
	v_add_f32_e32 v52, v121, v0
	v_mul_f32_e32 v0, v121, v121
	v_pk_add_f32 v[50:51], v[0:1], v[50:51] op_sel_hi:[0,1]
	v_add_f32_e32 v0, v122, v52
	v_lshlrev_b32_e32 v52, 16, v126
	v_and_b32_e32 v53, 0xffff0000, v126
	s_waitcnt vmcnt(40)
	v_lshlrev_b32_e32 v54, 16, v128
	v_and_b32_e32 v55, 0xffff0000, v128
	v_pk_add_f32 v[52:53], v[52:53], v[54:55]
	v_pk_fma_f32 v[50:51], v[122:123], v[122:123], v[50:51]
	v_add_f32_e32 v56, v123, v0
	v_mul_f32_e32 v0, v123, v123
	v_pk_add_f32 v[124:125], v[62:63], v[52:53]
	v_lshlrev_b32_e32 v52, 16, v127
	v_and_b32_e32 v53, 0xffff0000, v127
	v_lshlrev_b32_e32 v54, 16, v129
	v_and_b32_e32 v55, 0xffff0000, v129
	v_pk_add_f32 v[50:51], v[0:1], v[50:51] op_sel_hi:[0,1]
	v_pk_add_f32 v[52:53], v[52:53], v[54:55]
	v_add_f32_e32 v0, v124, v56
	v_pk_add_f32 v[126:127], v[64:65], v[52:53]
	v_pk_fma_f32 v[50:51], v[124:125], v[124:125], v[50:51]
	v_add_f32_e32 v52, v125, v0
	v_mul_f32_e32 v0, v125, v125
	v_pk_add_f32 v[50:51], v[0:1], v[50:51] op_sel_hi:[0,1]
	v_add_f32_e32 v0, v126, v52
	s_waitcnt vmcnt(35)
	v_lshlrev_b32_e32 v52, 16, v130
	v_and_b32_e32 v53, 0xffff0000, v130
	s_waitcnt vmcnt(31)
	v_lshlrev_b32_e32 v54, 16, v132
	v_and_b32_e32 v55, 0xffff0000, v132
	v_pk_add_f32 v[52:53], v[52:53], v[54:55]
	v_pk_fma_f32 v[50:51], v[126:127], v[126:127], v[50:51]
	v_add_f32_e32 v56, v127, v0
	v_mul_f32_e32 v0, v127, v127
	v_pk_add_f32 v[128:129], v[34:35], v[52:53]
	v_lshlrev_b32_e32 v34, 16, v131
	v_and_b32_e32 v35, 0xffff0000, v131
	v_lshlrev_b32_e32 v52, 16, v133
	v_and_b32_e32 v53, 0xffff0000, v133
	v_pk_add_f32 v[50:51], v[0:1], v[50:51] op_sel_hi:[0,1]
	v_pk_add_f32 v[34:35], v[34:35], v[52:53]
	v_add_f32_e32 v0, v128, v56
	v_pk_add_f32 v[130:131], v[36:37], v[34:35]
	v_pk_fma_f32 v[34:35], v[128:129], v[128:129], v[50:51]
	v_add_f32_e32 v36, v129, v0
	v_mul_f32_e32 v0, v129, v129
	v_pk_add_f32 v[34:35], v[0:1], v[34:35] op_sel_hi:[0,1]
	v_add_f32_e32 v0, v130, v36
	v_lshlrev_b32_e32 v36, 16, v134
	v_and_b32_e32 v37, 0xffff0000, v134
	s_waitcnt vmcnt(30)
	v_lshlrev_b32_e32 v50, 16, v136
	v_and_b32_e32 v51, 0xffff0000, v136
	v_pk_add_f32 v[36:37], v[36:37], v[50:51]
	v_pk_fma_f32 v[34:35], v[130:131], v[130:131], v[34:35]
	v_add_f32_e32 v52, v131, v0
	v_mul_f32_e32 v0, v131, v131
	v_pk_add_f32 v[132:133], v[38:39], v[36:37]
	v_lshlrev_b32_e32 v36, 16, v135
	v_and_b32_e32 v37, 0xffff0000, v135
	v_lshlrev_b32_e32 v38, 16, v137
	v_and_b32_e32 v39, 0xffff0000, v137
	v_pk_add_f32 v[34:35], v[0:1], v[34:35] op_sel_hi:[0,1]
	v_pk_add_f32 v[36:37], v[36:37], v[38:39]
	v_add_f32_e32 v0, v132, v52
	v_pk_add_f32 v[134:135], v[40:41], v[36:37]
	v_pk_fma_f32 v[34:35], v[132:133], v[132:133], v[34:35]
	v_add_f32_e32 v36, v133, v0
	v_mul_f32_e32 v0, v133, v133
	v_pk_add_f32 v[34:35], v[0:1], v[34:35] op_sel_hi:[0,1]
	v_add_f32_e32 v0, v134, v36
	v_lshlrev_b32_e32 v36, 16, v138
	v_and_b32_e32 v37, 0xffff0000, v138
	s_waitcnt vmcnt(29)
	v_lshlrev_b32_e32 v38, 16, v140
	v_and_b32_e32 v39, 0xffff0000, v140
	v_pk_add_f32 v[36:37], v[36:37], v[38:39]
	v_pk_fma_f32 v[34:35], v[134:135], v[134:135], v[34:35]
	v_add_f32_e32 v40, v135, v0
	v_mul_f32_e32 v0, v135, v135
	v_pk_add_f32 v[136:137], v[42:43], v[36:37]
	v_lshlrev_b32_e32 v36, 16, v139
	v_and_b32_e32 v37, 0xffff0000, v139
	v_lshlrev_b32_e32 v38, 16, v141
	v_and_b32_e32 v39, 0xffff0000, v141
	v_pk_add_f32 v[34:35], v[0:1], v[34:35] op_sel_hi:[0,1]
	v_pk_add_f32 v[36:37], v[36:37], v[38:39]
	v_add_f32_e32 v0, v136, v40
	v_pk_add_f32 v[138:139], v[44:45], v[36:37]
	v_pk_fma_f32 v[34:35], v[136:137], v[136:137], v[34:35]
	v_add_f32_e32 v36, v137, v0
	v_mul_f32_e32 v0, v137, v137
	v_pk_add_f32 v[34:35], v[0:1], v[34:35] op_sel_hi:[0,1]
	v_add_f32_e32 v0, v138, v36
	v_lshlrev_b32_e32 v36, 16, v142
	v_and_b32_e32 v37, 0xffff0000, v142
	s_waitcnt vmcnt(28)
	v_lshlrev_b32_e32 v38, 16, v144
	v_and_b32_e32 v39, 0xffff0000, v144
	v_pk_add_f32 v[36:37], v[36:37], v[38:39]
	v_pk_fma_f32 v[34:35], v[138:139], v[138:139], v[34:35]
	v_add_f32_e32 v40, v139, v0
	v_mul_f32_e32 v0, v139, v139
	v_pk_add_f32 v[140:141], v[46:47], v[36:37]
	v_lshlrev_b32_e32 v36, 16, v143
	v_and_b32_e32 v37, 0xffff0000, v143
	v_lshlrev_b32_e32 v38, 16, v145
	v_and_b32_e32 v39, 0xffff0000, v145
	v_pk_add_f32 v[34:35], v[0:1], v[34:35] op_sel_hi:[0,1]
	v_pk_add_f32 v[36:37], v[36:37], v[38:39]
	v_add_f32_e32 v0, v140, v40
	v_pk_add_f32 v[142:143], v[48:49], v[36:37]
	v_pk_fma_f32 v[34:35], v[140:141], v[140:141], v[34:35]
	v_add_f32_e32 v36, v141, v0
	v_mul_f32_e32 v0, v141, v141
	v_pk_add_f32 v[34:35], v[0:1], v[34:35] op_sel_hi:[0,1]
	v_add_f32_e32 v0, v142, v36
	s_waitcnt vmcnt(23)
	v_lshlrev_b32_e32 v36, 16, v146
	v_and_b32_e32 v37, 0xffff0000, v146
	s_waitcnt vmcnt(19)
	v_lshlrev_b32_e32 v38, 16, v148
	v_and_b32_e32 v39, 0xffff0000, v148
	v_pk_add_f32 v[36:37], v[36:37], v[38:39]
	v_pk_fma_f32 v[34:35], v[142:143], v[142:143], v[34:35]
	v_add_f32_e32 v40, v143, v0
	v_mul_f32_e32 v0, v143, v143
	v_pk_add_f32 v[144:145], v[18:19], v[36:37]
	v_lshlrev_b32_e32 v18, 16, v147
	v_and_b32_e32 v19, 0xffff0000, v147
	v_lshlrev_b32_e32 v36, 16, v149
	v_and_b32_e32 v37, 0xffff0000, v149
	v_pk_add_f32 v[34:35], v[0:1], v[34:35] op_sel_hi:[0,1]
	v_pk_add_f32 v[18:19], v[18:19], v[36:37]
	v_add_f32_e32 v0, v144, v40
	v_pk_add_f32 v[146:147], v[20:21], v[18:19]
	v_pk_fma_f32 v[18:19], v[144:145], v[144:145], v[34:35]
	v_add_f32_e32 v20, v145, v0
	v_mul_f32_e32 v0, v145, v145
	v_pk_add_f32 v[18:19], v[0:1], v[18:19] op_sel_hi:[0,1]
	v_add_f32_e32 v0, v146, v20
	v_lshlrev_b32_e32 v20, 16, v150
	v_and_b32_e32 v21, 0xffff0000, v150
	s_waitcnt vmcnt(18)
	v_lshlrev_b32_e32 v34, 16, v152
	v_and_b32_e32 v35, 0xffff0000, v152
	v_pk_add_f32 v[20:21], v[20:21], v[34:35]
	v_pk_fma_f32 v[18:19], v[146:147], v[146:147], v[18:19]
	v_add_f32_e32 v36, v147, v0
	v_mul_f32_e32 v0, v147, v147
	v_pk_add_f32 v[148:149], v[22:23], v[20:21]
	v_lshlrev_b32_e32 v20, 16, v151
	v_and_b32_e32 v21, 0xffff0000, v151
	v_lshlrev_b32_e32 v22, 16, v153
	v_and_b32_e32 v23, 0xffff0000, v153
	v_pk_add_f32 v[18:19], v[0:1], v[18:19] op_sel_hi:[0,1]
	v_pk_add_f32 v[20:21], v[20:21], v[22:23]
	v_add_f32_e32 v0, v148, v36
	v_pk_add_f32 v[150:151], v[24:25], v[20:21]
	v_pk_fma_f32 v[18:19], v[148:149], v[148:149], v[18:19]
	v_add_f32_e32 v20, v149, v0
	v_mul_f32_e32 v0, v149, v149
	v_pk_add_f32 v[18:19], v[0:1], v[18:19] op_sel_hi:[0,1]
	v_add_f32_e32 v0, v150, v20
	v_lshlrev_b32_e32 v20, 16, v154
	v_and_b32_e32 v21, 0xffff0000, v154
	s_waitcnt vmcnt(17)
	v_lshlrev_b32_e32 v22, 16, v156
	v_and_b32_e32 v23, 0xffff0000, v156
	v_pk_add_f32 v[20:21], v[20:21], v[22:23]
	v_pk_fma_f32 v[18:19], v[150:151], v[150:151], v[18:19]
	v_add_f32_e32 v24, v151, v0
	v_mul_f32_e32 v0, v151, v151
	v_pk_add_f32 v[152:153], v[26:27], v[20:21]
	v_lshlrev_b32_e32 v20, 16, v155
	v_and_b32_e32 v21, 0xffff0000, v155
	v_lshlrev_b32_e32 v22, 16, v157
	v_and_b32_e32 v23, 0xffff0000, v157
	v_pk_add_f32 v[18:19], v[0:1], v[18:19] op_sel_hi:[0,1]
	v_pk_add_f32 v[20:21], v[20:21], v[22:23]
	v_add_f32_e32 v0, v152, v24
	v_pk_add_f32 v[154:155], v[28:29], v[20:21]
	v_pk_fma_f32 v[18:19], v[152:153], v[152:153], v[18:19]
	v_add_f32_e32 v20, v153, v0
	v_mul_f32_e32 v0, v153, v153
	v_pk_add_f32 v[18:19], v[0:1], v[18:19] op_sel_hi:[0,1]
	v_add_f32_e32 v0, v154, v20
	v_lshlrev_b32_e32 v20, 16, v158
	v_and_b32_e32 v21, 0xffff0000, v158
	s_waitcnt vmcnt(16)
	v_lshlrev_b32_e32 v22, 16, v160
	v_and_b32_e32 v23, 0xffff0000, v160
	v_pk_add_f32 v[20:21], v[20:21], v[22:23]
	v_pk_fma_f32 v[18:19], v[154:155], v[154:155], v[18:19]
	v_add_f32_e32 v24, v155, v0
	v_mul_f32_e32 v0, v155, v155
	v_pk_add_f32 v[156:157], v[30:31], v[20:21]
	v_lshlrev_b32_e32 v20, 16, v159
	v_and_b32_e32 v21, 0xffff0000, v159
	v_lshlrev_b32_e32 v22, 16, v161
	v_and_b32_e32 v23, 0xffff0000, v161
	v_pk_add_f32 v[18:19], v[0:1], v[18:19] op_sel_hi:[0,1]
	v_pk_add_f32 v[20:21], v[20:21], v[22:23]
	v_add_f32_e32 v0, v156, v24
	v_pk_add_f32 v[158:159], v[32:33], v[20:21]
	v_pk_fma_f32 v[18:19], v[156:157], v[156:157], v[18:19]
	v_add_f32_e32 v20, v157, v0
	v_mul_f32_e32 v0, v157, v157
	v_pk_add_f32 v[18:19], v[0:1], v[18:19] op_sel_hi:[0,1]
	v_add_f32_e32 v0, v158, v20
	s_waitcnt vmcnt(11)
	v_lshlrev_b32_e32 v20, 16, v162
	v_and_b32_e32 v21, 0xffff0000, v162
	s_waitcnt vmcnt(7)
	v_lshlrev_b32_e32 v22, 16, v166
	v_and_b32_e32 v23, 0xffff0000, v166
	v_pk_add_f32 v[20:21], v[20:21], v[22:23]
	v_pk_fma_f32 v[18:19], v[158:159], v[158:159], v[18:19]
	v_add_f32_e32 v24, v159, v0
	v_mul_f32_e32 v0, v159, v159
	v_pk_add_f32 v[160:161], v[2:3], v[20:21]
	v_lshlrev_b32_e32 v2, 16, v163
	v_and_b32_e32 v3, 0xffff0000, v163
	v_lshlrev_b32_e32 v20, 16, v167
	v_and_b32_e32 v21, 0xffff0000, v167
	v_pk_add_f32 v[18:19], v[0:1], v[18:19] op_sel_hi:[0,1]
	v_pk_add_f32 v[2:3], v[2:3], v[20:21]
	v_add_f32_e32 v0, v160, v24
	v_pk_add_f32 v[162:163], v[4:5], v[2:3]
	v_pk_fma_f32 v[2:3], v[160:161], v[160:161], v[18:19]
	v_add_f32_e32 v4, v161, v0
	v_mul_f32_e32 v0, v161, v161
	v_pk_add_f32 v[2:3], v[0:1], v[2:3] op_sel_hi:[0,1]
	v_add_f32_e32 v0, v162, v4
	v_lshlrev_b32_e32 v4, 16, v164
	v_and_b32_e32 v5, 0xffff0000, v164
	s_waitcnt vmcnt(6)
	v_lshlrev_b32_e32 v18, 16, v170
	v_and_b32_e32 v19, 0xffff0000, v170
	v_pk_add_f32 v[4:5], v[4:5], v[18:19]
	v_add_f32_e32 v0, v163, v0
	v_pk_add_f32 v[166:167], v[6:7], v[4:5]
	v_lshlrev_b32_e32 v4, 16, v165
	v_and_b32_e32 v5, 0xffff0000, v165
	v_lshlrev_b32_e32 v6, 16, v171
	v_and_b32_e32 v7, 0xffff0000, v171
	v_pk_fma_f32 v[2:3], v[162:163], v[162:163], v[2:3]
	v_pk_add_f32 v[4:5], v[4:5], v[6:7]
	v_add_f32_e32 v6, v166, v0
	v_mul_f32_e32 v0, v163, v163
	v_pk_add_f32 v[164:165], v[8:9], v[4:5]
	v_mov_b32_e32 v4, v166
	v_mov_b32_e32 v5, v163
	v_pk_add_f32 v[2:3], v[0:1], v[2:3] op_sel_hi:[0,1]
	v_add_f32_e32 v0, v167, v6
	v_pk_fma_f32 v[2:3], v[4:5], v[4:5], v[2:3]
	v_add_f32_e32 v6, v164, v0
	v_mul_f32_e32 v0, v167, v167
	v_mov_b32_e32 v4, v164
	v_mov_b32_e32 v5, v167
	v_pk_add_f32 v[2:3], v[0:1], v[2:3] op_sel_hi:[0,1]
	v_pk_fma_f32 v[2:3], v[4:5], v[4:5], v[2:3]
	v_add_f32_e32 v0, v165, v6
	v_lshlrev_b32_e32 v4, 16, v168
	v_and_b32_e32 v5, 0xffff0000, v168
	s_waitcnt vmcnt(5)
	v_lshlrev_b32_e32 v6, 16, v174
	v_and_b32_e32 v7, 0xffff0000, v174
	v_pk_add_f32 v[4:5], v[4:5], v[6:7]
	v_lshlrev_b32_e32 v6, 16, v175
	v_pk_add_f32 v[170:171], v[10:11], v[4:5]
	v_lshlrev_b32_e32 v4, 16, v169
	v_and_b32_e32 v5, 0xffff0000, v169
	v_and_b32_e32 v7, 0xffff0000, v175
	v_pk_add_f32 v[4:5], v[4:5], v[6:7]
	v_add_f32_e32 v6, v170, v0
	v_mul_f32_e32 v0, v165, v165
	v_pk_add_f32 v[168:169], v[12:13], v[4:5]
	v_mov_b32_e32 v4, v170
	v_mov_b32_e32 v5, v165
	v_pk_add_f32 v[2:3], v[0:1], v[2:3] op_sel_hi:[0,1]
	v_add_f32_e32 v0, v171, v6
	v_pk_fma_f32 v[2:3], v[4:5], v[4:5], v[2:3]
	v_add_f32_e32 v6, v168, v0
	v_mul_f32_e32 v0, v171, v171
	v_mov_b32_e32 v4, v168
	v_mov_b32_e32 v5, v171
	v_pk_add_f32 v[2:3], v[0:1], v[2:3] op_sel_hi:[0,1]
	v_pk_fma_f32 v[2:3], v[4:5], v[4:5], v[2:3]
	v_add_f32_e32 v77, v169, v6
	v_lshlrev_b32_e32 v4, 16, v172
	v_and_b32_e32 v5, 0xffff0000, v172
	s_waitcnt vmcnt(4)
	v_lshlrev_b32_e32 v6, 16, v176
	v_and_b32_e32 v7, 0xffff0000, v176
	v_pk_add_f32 v[4:5], v[4:5], v[6:7]
	v_lshlrev_b32_e32 v6, 16, v177
	v_pk_add_f32 v[174:175], v[14:15], v[4:5]
	v_lshlrev_b32_e32 v4, 16, v173
	v_and_b32_e32 v5, 0xffff0000, v173
	v_and_b32_e32 v7, 0xffff0000, v177
	v_pk_add_f32 v[4:5], v[4:5], v[6:7]
	v_mul_f32_e32 v0, v169, v169
	v_pk_add_f32 v[172:173], v[16:17], v[4:5]
	v_mov_b32_e32 v4, v174
	v_mov_b32_e32 v5, v169
	v_pk_add_f32 v[2:3], v[0:1], v[2:3] op_sel_hi:[0,1]
	v_pk_fma_f32 v[2:3], v[4:5], v[4:5], v[2:3]
	v_mul_f32_e32 v0, v175, v175
	v_mov_b32_e32 v4, v172
	v_mov_b32_e32 v5, v175
	v_pk_add_f32 v[2:3], v[0:1], v[2:3] op_sel_hi:[0,1]
	v_lshlrev_b32_e32 v0, 11, v226
	v_pk_fma_f32 v[178:179], v[4:5], v[4:5], v[2:3]
	v_lshl_add_u64 v[2:3], v[72:73], 0, v[0:1]
	global_load_dwordx4 v[62:65], v[2:3], off
	global_load_dwordx4 v[58:61], v[2:3], off offset:32
	global_load_dwordx4 v[54:57], v[2:3], off offset:64
	global_load_dwordx4 v[50:53], v[2:3], off offset:96
	global_load_dwordx4 v[46:49], v[2:3], off offset:128
	global_load_dwordx4 v[42:45], v[2:3], off offset:160
	global_load_dwordx4 v[38:41], v[2:3], off offset:192
	global_load_dwordx4 v[34:37], v[2:3], off offset:224
	global_load_dwordx4 v[30:33], v[2:3], off offset:256
	global_load_dwordx4 v[26:29], v[2:3], off offset:288
	global_load_dwordx4 v[22:25], v[2:3], off offset:320
	global_load_dwordx4 v[18:21], v[2:3], off offset:352
	global_load_dwordx4 v[14:17], v[2:3], off offset:384
	global_load_dwordx4 v[10:13], v[2:3], off offset:416
	global_load_dwordx4 v[6:9], v[2:3], off offset:448
	s_nop 0
	global_load_dwordx4 v[2:5], v[2:3], off offset:480
	v_add_f32_e32 v0, v174, v77
	v_pk_mul_f32 v[176:177], v[172:173], v[172:173]
	v_add_f32_e32 v0, v175, v0
	v_add_f32_e32 v176, v172, v0
	v_pk_mov_b32 v[178:179], v[172:173], v[178:179] op_sel:[1,0]
	s_nop 0
	v_pk_add_f32 v[176:177], v[178:179], v[176:177]
	ds_bpermute_b32 v178, v192, v176
	ds_bpermute_b32 v179, v192, v177
	s_and_saveexec_b64 s[4:5], vcc
	s_cbranch_execz .LBB0_387
	s_waitcnt lgkmcnt(0)
	v_pk_add_f32 v[176:177], v[176:177], v[178:179]
	ds_write_b64 v193, v[176:177] offset:8192
	s_branch .LBB0_387
